# fox: waves whose rows see the whole diagonal tile take the unmasked fast path
# baseline (speedup 1.0000x reference)
; DI f32x4 mmaT(bf16x8 a_m, bf16x8 b_n, f32x4 c) { return __builtin_amdgcn_mfma_f32_16x16x32_bf16(b_n, a_m, c, 0, 0, 0); }
; DI v4i16_t tr_rd(const bf16_t* a) { return __builtin_amdgcn_ds_read_tr16_b64_v4i16((LDSP v4i16_t*)a); }
; template <bool DIAG>
; DI void fox_tile(const bf16_t* sK, const bf16_t* sV, const float* sFk, const bf16x8 (&qf)[2][2], f32x4 (&o)[2][4], float (&mrun)[2], float (&lsum)[2], int key0, int qg0, int fr, int fq, int lane) {
;   const float SC2 = 0.125f * LOG2E;
;   f32x4 s[2][4];
;   const int kof = (fr * 64 + fq * 16) ^ ((fr >> 3) << 5);
; #pragma unroll
;   for (int t = 0; t < 4; ++t) {
;     const bf16x8 k0 = *(const bf16x8*)((const unsigned char*)sK + (t * 2) * 1024 + kof), k1 = *(const bf16x8*)((const unsigned char*)sK + (t * 2 + 1) * 1024 + kof);
; #pragma unroll
;     for (int mi = 0; mi < 2; ++mi) { s[mi][t] = mmaT(qf[mi][0], k0, (f32x4){0.f, 0.f, 0.f, 0.f}); s[mi][t] = mmaT(qf[mi][1], k1, s[mi][t]); }
;   }
;   f32x4 fk[4];
; #pragma unroll
;   for (int t = 0; t < 4; ++t) fk[t] = *(const f32x4*)(sFk + 16 * t + 4 * fq);
;   __builtin_amdgcn_sched_barrier(0);
;   bf16x8 vf[2][4];
; #pragma unroll
;   for (int k2 = 0; k2 < 2; ++k2)
; #pragma unroll
;     for (int d = 0; d < 4; ++d) {
;       const bf16_t* a = sV + (32 * k2 + 4 * fq + (fr >> 2)) * 72 + 16 * d + 4 * (fr & 3);
;       const v4i16_t lo = tr_rd(a), hi = tr_rd(a + 16 * 72);
;       vf[k2][d] = __builtin_shufflevector(lo, hi, 0, 1, 2, 3, 4, 5, 6, 7);
;     }
;   __builtin_amdgcn_sched_barrier(0);
; DI void fox_unit(const Params& p, int hf, int bl, int fh, int qb, unsigned char* shm, int tid, bool dry = false) {
;     ...
;     if (kt * 64 <= q0 + wid * 32 + 31) {
;       if (kt >= 4 * qb) fox_tile<true>(sK, sV, sFk, qf, o, mrun, lsum, kt * 64, qg0, fr, fq, lane);
;       else fox_tile<false>(sK, sV, sFk, qf, o, mrun, lsum, kt * 64, qg0, fr, fq, lane);
.LBB0_489:
	s_mul_i32 s4, s21, 0x4900
	s_add_i32 s4, s4, 32
	v_add_u32_e32 v24, s4, v213
	ds_read_b128 v[64:67], v24
	ds_read_b128 v[68:71], v24 offset:1024
	ds_read_b128 v[56:59], v24 offset:2048
	ds_read_b128 v[60:63], v24 offset:3072
	ds_read_b128 v[48:51], v24 offset:4096
	ds_read_b128 v[52:55], v24 offset:5120
	ds_read_b128 v[40:43], v24 offset:6144
	ds_read_b128 v[44:47], v24 offset:7168
	v_lshl_add_u32 v24, v209, 2, s4
	ds_read_b128 v[36:39], v24 offset:18432
	ds_read_b128 v[32:35], v24 offset:18496
	ds_read_b128 v[28:31], v24 offset:18560
	ds_read_b128 v[24:27], v24 offset:18624
	v_lshl_add_u32 v72, v214, 1, s4
	v_readfirstlane_b32 s100, v212
	s_add_i32 s101, s18, 94
	s_mov_b64 s[4:5], -1
	v_add_u32_e32 v221, v72, v215
	s_cmp_le_i32 s101, s100
	s_cbranch_scc1 .LBB0_491
	s_waitcnt lgkmcnt(11)
	v_mfma_f32_16x16x32_bf16 v[72:75], v[64:67], v[0:3], 0
	s_waitcnt lgkmcnt(10)
	v_mfma_f32_16x16x32_bf16 v[146:149], v[68:71], v[4:7], v[72:75]
	v_mfma_f32_16x16x32_bf16 v[72:75], v[64:67], v[8:11], 0
	v_mfma_f32_16x16x32_bf16 v[164:167], v[68:71], v[12:15], v[72:75]
	s_waitcnt lgkmcnt(9)
	v_mfma_f32_16x16x32_bf16 v[72:75], v[56:59], v[0:3], 0
	s_waitcnt lgkmcnt(8)
	v_mfma_f32_16x16x32_bf16 v[150:153], v[60:63], v[4:7], v[72:75]
	v_mfma_f32_16x16x32_bf16 v[72:75], v[56:59], v[8:11], 0
	v_mfma_f32_16x16x32_bf16 v[222:225], v[60:63], v[12:15], v[72:75]
	s_waitcnt lgkmcnt(7)
	v_mfma_f32_16x16x32_bf16 v[72:75], v[48:51], v[0:3], 0
	s_waitcnt lgkmcnt(6)
	v_mfma_f32_16x16x32_bf16 v[154:157], v[52:55], v[4:7], v[72:75]
	v_mfma_f32_16x16x32_bf16 v[72:75], v[48:51], v[8:11], 0
	v_mfma_f32_16x16x32_bf16 v[226:229], v[52:55], v[12:15], v[72:75]
	s_waitcnt lgkmcnt(5)
	v_mfma_f32_16x16x32_bf16 v[72:75], v[40:43], v[0:3], 0
	s_waitcnt lgkmcnt(4)
	v_mfma_f32_16x16x32_bf16 v[172:175], v[44:47], v[4:7], v[72:75]
	v_mfma_f32_16x16x32_bf16 v[72:75], v[40:43], v[8:11], 0
	v_mfma_f32_16x16x32_bf16 v[104:107], v[44:47], v[12:15], v[72:75]
	ds_read_b64_tr_b16 v[100:101], v221 offset:9216
	ds_read_b64_tr_b16 v[92:93], v221 offset:9248
	ds_read_b64_tr_b16 v[96:97], v221 offset:9280
	ds_read_b64_tr_b16 v[88:89], v221 offset:9312
	ds_read_b64_tr_b16 v[102:103], v221 offset:11520
	ds_read_b64_tr_b16 v[94:95], v221 offset:11552
	ds_read_b64_tr_b16 v[98:99], v221 offset:11584
	ds_read_b64_tr_b16 v[90:91], v221 offset:11616
	ds_read_b64_tr_b16 v[84:85], v221 offset:13824
	ds_read_b64_tr_b16 v[80:81], v221 offset:13856
	ds_read_b64_tr_b16 v[76:77], v221 offset:13888
	ds_read_b64_tr_b16 v[72:73], v221 offset:13920
	ds_read_b64_tr_b16 v[86:87], v221 offset:16128
	ds_read_b64_tr_b16 v[82:83], v221 offset:16160
	ds_read_b64_tr_b16 v[78:79], v221 offset:16192
	ds_read_b64_tr_b16 v[74:75], v221 offset:16224
	s_cmp_eq_u32 s99, 0
	s_cbranch_scc1 .Lfox1_nm1
	s_barrier

; DI f32x4 mmaT(bf16x8 a_m, bf16x8 b_n, f32x4 c) { return __builtin_amdgcn_mfma_f32_16x16x32_bf16(b_n, a_m, c, 0, 0, 0); }
; DI v4i16_t tr_rd(const bf16_t* a) { return __builtin_amdgcn_ds_read_tr16_b64_v4i16((LDSP v4i16_t*)a); }
; template <bool DIAG>
; DI void fox_tile(const bf16_t* sK, const bf16_t* sV, const float* sFk, const bf16x8 (&qf)[2][2], f32x4 (&o)[2][4], float (&mrun)[2], float (&lsum)[2], int key0, int qg0, int fr, int fq, int lane) {
;   const float SC2 = 0.125f * LOG2E;
;   f32x4 s[2][4];
;   const int kof = (fr * 64 + fq * 16) ^ ((fr >> 3) << 5);
; #pragma unroll
;   for (int t = 0; t < 4; ++t) {
;     const bf16x8 k0 = *(const bf16x8*)((const unsigned char*)sK + (t * 2) * 1024 + kof), k1 = *(const bf16x8*)((const unsigned char*)sK + (t * 2 + 1) * 1024 + kof);
; #pragma unroll
;     for (int mi = 0; mi < 2; ++mi) { s[mi][t] = mmaT(qf[mi][0], k0, (f32x4){0.f, 0.f, 0.f, 0.f}); s[mi][t] = mmaT(qf[mi][1], k1, s[mi][t]); }
;   }
;   f32x4 fk[4];
; #pragma unroll
;   for (int t = 0; t < 4; ++t) fk[t] = *(const f32x4*)(sFk + 16 * t + 4 * fq);
;   __builtin_amdgcn_sched_barrier(0);
;   bf16x8 vf[2][4];
; #pragma unroll
;   for (int k2 = 0; k2 < 2; ++k2)
; #pragma unroll
;     for (int d = 0; d < 4; ++d) {
;       const bf16_t* a = sV + (32 * k2 + 4 * fq + (fr >> 2)) * 72 + 16 * d + 4 * (fr & 3);
;       const v4i16_t lo = tr_rd(a), hi = tr_rd(a + 16 * 72);
;       vf[k2][d] = __builtin_shufflevector(lo, hi, 0, 1, 2, 3, 4, 5, 6, 7);
;     }
;   __builtin_amdgcn_sched_barrier(0);
; DI void fox_unit(const Params& p, int hf, int bl, int fh, int qb, unsigned char* shm, int tid, bool dry = false) {
;     ...
;     if (kt * 64 <= q0 + wid * 32 + 31) {
;       if (kt >= 4 * qb) fox_tile<true>(sK, sV, sFk, qf, o, mrun, lsum, kt * 64, qg0, fr, fq, lane);
;       else fox_tile<false>(sK, sV, sFk, qf, o, mrun, lsum, kt * 64, qg0, fr, fq, lane);
.LBB0_609:
	s_mul_i32 s4, s20, 0x4900
	s_add_i32 s4, s4, 32
	v_add_u32_e32 v24, s4, v213
	ds_read_b128 v[64:67], v24
	ds_read_b128 v[68:71], v24 offset:1024
	ds_read_b128 v[56:59], v24 offset:2048
	ds_read_b128 v[60:63], v24 offset:3072
	ds_read_b128 v[48:51], v24 offset:4096
	ds_read_b128 v[52:55], v24 offset:5120
	ds_read_b128 v[40:43], v24 offset:6144
	ds_read_b128 v[44:47], v24 offset:7168
	v_lshl_add_u32 v24, v209, 2, s4
	ds_read_b128 v[36:39], v24 offset:18432
	ds_read_b128 v[32:35], v24 offset:18496
	ds_read_b128 v[28:31], v24 offset:18560
	ds_read_b128 v[24:27], v24 offset:18624
	v_lshl_add_u32 v72, v214, 1, s4
	v_readfirstlane_b32 s100, v212
	s_add_i32 s101, s17, 94
	s_mov_b64 s[4:5], -1
	v_add_u32_e32 v221, v72, v215
	s_cmp_le_i32 s101, s100
	s_cbranch_scc1 .LBB0_611
	s_waitcnt lgkmcnt(11)
	v_mfma_f32_16x16x32_bf16 v[72:75], v[64:67], v[0:3], 0
	s_waitcnt lgkmcnt(10)
	v_mfma_f32_16x16x32_bf16 v[146:149], v[68:71], v[4:7], v[72:75]
	v_mfma_f32_16x16x32_bf16 v[72:75], v[64:67], v[8:11], 0
	v_mfma_f32_16x16x32_bf16 v[222:225], v[68:71], v[12:15], v[72:75]
	s_waitcnt lgkmcnt(9)
	v_mfma_f32_16x16x32_bf16 v[72:75], v[56:59], v[0:3], 0
	s_waitcnt lgkmcnt(8)
	v_mfma_f32_16x16x32_bf16 v[150:153], v[60:63], v[4:7], v[72:75]
	v_mfma_f32_16x16x32_bf16 v[72:75], v[56:59], v[8:11], 0
	v_mfma_f32_16x16x32_bf16 v[226:229], v[60:63], v[12:15], v[72:75]
	s_waitcnt lgkmcnt(7)
	v_mfma_f32_16x16x32_bf16 v[72:75], v[48:51], v[0:3], 0
	s_waitcnt lgkmcnt(6)
	v_mfma_f32_16x16x32_bf16 v[154:157], v[52:55], v[4:7], v[72:75]
	v_mfma_f32_16x16x32_bf16 v[72:75], v[48:51], v[8:11], 0
	v_mfma_f32_16x16x32_bf16 v[230:233], v[52:55], v[12:15], v[72:75]
	s_waitcnt lgkmcnt(5)
	v_mfma_f32_16x16x32_bf16 v[72:75], v[40:43], v[0:3], 0
	s_waitcnt lgkmcnt(4)
	v_mfma_f32_16x16x32_bf16 v[172:175], v[44:47], v[4:7], v[72:75]
	v_mfma_f32_16x16x32_bf16 v[72:75], v[40:43], v[8:11], 0
	v_mfma_f32_16x16x32_bf16 v[104:107], v[44:47], v[12:15], v[72:75]
	ds_read_b64_tr_b16 v[100:101], v221 offset:9216
	ds_read_b64_tr_b16 v[92:93], v221 offset:9248
	ds_read_b64_tr_b16 v[96:97], v221 offset:9280
	ds_read_b64_tr_b16 v[88:89], v221 offset:9312
	ds_read_b64_tr_b16 v[102:103], v221 offset:11520
	ds_read_b64_tr_b16 v[94:95], v221 offset:11552
	ds_read_b64_tr_b16 v[98:99], v221 offset:11584
	ds_read_b64_tr_b16 v[90:91], v221 offset:11616
	ds_read_b64_tr_b16 v[84:85], v221 offset:13824
	ds_read_b64_tr_b16 v[80:81], v221 offset:13856
	ds_read_b64_tr_b16 v[76:77], v221 offset:13888
	ds_read_b64_tr_b16 v[72:73], v221 offset:13920
	ds_read_b64_tr_b16 v[86:87], v221 offset:16128
	ds_read_b64_tr_b16 v[82:83], v221 offset:16160
	ds_read_b64_tr_b16 v[78:79], v221 offset:16192
	ds_read_b64_tr_b16 v[74:75], v221 offset:16224
	s_cmp_eq_u32 s99, 0
	s_cbranch_scc1 .Lfox2_nm1
	s_barrier
